# 4-bit K-tile XOR swizzle also in memory cross-attention (P3), on top of the MLA attention swizzle
# baseline (speedup 1.0000x reference)
; template <int NCB> DEVFI int v_st(int k, int c) { const int kk = (k & ~0xC) | ((k & 4) << 1) | ((k & 8) >> 1); return ((kk >> 3) * NCB + (c >> 5)) * 512 + ((kk & 7) * 32 + (c & 31)) * 2; }
; DEVFI int v_rd_base(int lane) { return ((lane & 3) << 3) | (((lane >> 2) & 3) << 6) | (((lane >> 4) & 1) << 5) | (((lane >> 5) & 1) << 8); }
; #define QKT(P0, P1, KP) do { if constexpr (PRE) qkt<ND0>(P0, P1, KP, qr, r32, hi, negm); else qkt<ND0>(P0, P1, KP, qr, r32, hi); } while (0)
; #define PSM(P0, P1, MN, AL, FIRST) do { if constexpr (PRE) partialSM2(P0, P1, m_reg, negm, AL, thr2, FIRST); else partialSM(P0, P1, m_reg, MN, AL, C, thr_raw); } while (0)
; #define SWRITE(b, i) do { *(bf16x8*)(V_lds + (b) * SHM_V + vst0) = sr_[i].v0; if (V2) *(bf16x8*)(V_lds + (b) * SHM_V + vst1) = sr_[i].v1; \
;     *(bf16x8*)(K_lds + (b) * SHM_K + kst0) = sr_[i].k0; if (K2) { if (k1ok) *(bf16x8*)(K_lds + (b) * SHM_K + kst1) = sr_[i].k1; } } while (0)
; template <int DQK, int DV, bool PRE = false>
; DEVFI void attn_unit(const bf16_t* __restrict__ Qb, int ldq, const bf16_t* __restrict__ Kh, int ldk, const bf16_t* __restrict__ Vh, int ldv,
;                      bf16_t* __restrict__ Ob, int ldo, int seq, float scale, char* lds) {
;     ...
;     const int kst0 = KSWZ(kr0, kc0 * 2), kst1 = KSWZ(kr1, kc1 * 2), vst0 = v_st<NCB>(vr0, vc0), vst1 = v_st<NCB>(vr1, vc1);
;     const int vb0 = (int)(uintptr_t)V_lds + v_rd_base(lane);
;     struct { bf16x8 k0, k1, v0, v1; } sr_[2];
;     ...
;     f32x16 pA0, pA1, pB0, pB1; float mnA, mnB, alA, alB; bf16x8 pa0, pa1, pa2, pa3; const int NT = seq / KVBLK;
;     SLOAD(0, 0); asm volatile("s_waitcnt vmcnt(0)" ::: "memory"); SWRITE(0, 0); __syncthreads();
;     QKT(pA0, pA1, K_lds); PSM(pA0, pA1, mnA, alA, true);
;     SLOAD(1, KVBLK); if (2 < NT) SLOAD(0, 2 * KVBLK);
.LBB0_1048:
	s_or_b64 exec, exec, s[0:1]
	v_lshlrev_b32_e32 v24, 8, v60
	v_bitop3_b32 v25, v60, v20, 15 bitop3:0x6c
	v_lshl_add_u32 v26, v25, 4, v24
	v_lshlrev_b32_e32 v24, 8, v58
	v_bitop3_b32 v25, v58, v21, 15 bitop3:0x6c
	v_lshl_add_u32 v27, v25, 4, v24
	v_and_b32_e32 v24, 0xfffff0, v60
	v_lshlrev_b32_e32 v25, 1, v60
	v_and_or_b32 v24, v25, 8, v24
	v_lshrrev_b32_e32 v24, 1, v24
	v_lshrrev_b32_e32 v28, 2, v20
	v_lshrrev_b32_e32 v25, 1, v60
	v_add_u32_e32 v24, v24, v28
	v_and_b32_e32 v28, 3, v60
	v_lshlrev_b32_e32 v20, 4, v20
	v_and_or_b32 v25, v25, 4, v28
	v_and_b32_e32 v20, 48, v20
	v_lshl_or_b32 v20, v25, 6, v20
	v_lshl_or_b32 v28, v24, 9, v20
	v_and_b32_e32 v20, 0xfffff0, v58
	v_lshlrev_b32_e32 v24, 1, v58
	v_and_or_b32 v20, v24, 8, v20
	v_lshrrev_b32_e32 v20, 1, v20
	v_lshrrev_b32_e32 v25, 2, v21
	v_lshrrev_b32_e32 v24, 1, v58
	v_add_u32_e32 v20, v20, v25
	v_and_b32_e32 v25, 3, v58
	v_lshlrev_b32_e32 v21, 4, v21
	v_and_or_b32 v24, v24, 4, v25
	v_and_b32_e32 v21, 48, v21
	v_lshl_add_u64 v[22:23], s[12:13], 0, v[22:23]
	v_lshl_or_b32 v21, v24, 6, v21
	v_lshl_add_u64 v[22:23], v[66:67], 1, v[22:23]
	v_lshl_or_b32 v29, v20, 9, v21
	global_load_dwordx4 v[18:21], v[18:19], off offset:1024
	v_add_u32_e32 v186, 0, v28
	global_load_dwordx4 v[22:25], v[22:23], off offset:1024
	s_waitcnt vmcnt(0)
	v_add_u32_e32 v187, 0, v29
	v_add_u32_e32 v202, 0, v26
	v_add_u32_e32 v203, 0, v27
	s_waitcnt vmcnt(1)
	ds_write_b128 v186, v[18:21]
	s_waitcnt vmcnt(0)
	ds_write_b128 v187, v[22:25]
	ds_write_b128 v202, v[14:17] offset:32768
	s_and_saveexec_b64 s[0:1], s[44:45]
	ds_write_b128 v203, v[134:137] offset:32768
	s_or_b64 exec, exec, s[0:1]
	v_and_b32_e32 v175, 31, v188
	v_lshlrev_b32_e32 v14, 4, v175
	v_lshlrev_b32_e32 v56, 8, v175
	v_and_b32_e32 v57, 0xf0, v14
	v_bitop3_b32 v14, v174, v56, v57 bitop3:0xde
	v_add_u32_e32 v179, 0, v14
	s_waitcnt lgkmcnt(0)
	s_barrier
	ds_read_b128 v[14:17], v179 offset:32768
	v_or_b32_e32 v46, 32, v174
	v_bitop3_b32 v46, v46, v56, v57 bitop3:0xde
	v_add_u32_e32 v182, 0, v46
	ds_read_b128 v[46:49], v182 offset:32768
	s_waitcnt lgkmcnt(1)
	v_mfma_f32_32x32x16_bf16 v[30:45], v[14:17], v[126:129], 0
	ds_read_b128 v[14:17], v179 offset:40960
	v_or_b32_e32 v64, 0xc0, v174
	v_bitop3_b32 v64, v64, v56, v57 bitop3:0xde
	v_add_u32_e32 v185, 0, v64
	v_or_b32_e32 v64, 0xe0, v174
	s_mov_b64 s[0:1], exec
	s_waitcnt lgkmcnt(1)
	v_mfma_f32_32x32x16_bf16 v[30:45], v[46:49], v[122:125], v[30:45]
	ds_read_b128 v[46:49], v182 offset:40960
	s_waitcnt lgkmcnt(1)
	v_mfma_f32_32x32x16_bf16 v[14:29], v[14:17], v[126:129], 0
	s_waitcnt lgkmcnt(0)
	v_mfma_f32_32x32x16_bf16 v[14:29], v[46:49], v[122:125], v[14:29]
	v_or_b32_e32 v46, 64, v174
	v_bitop3_b32 v46, v46, v56, v57 bitop3:0xde
	v_add_u32_e32 v183, 0, v46
	ds_read_b128 v[46:49], v183 offset:32768
	s_waitcnt lgkmcnt(0)
	v_mfma_f32_32x32x16_bf16 v[30:45], v[46:49], v[118:121], v[30:45]
	ds_read_b128 v[46:49], v183 offset:40960
	s_waitcnt lgkmcnt(0)
	v_mfma_f32_32x32x16_bf16 v[14:29], v[46:49], v[118:121], v[14:29]
	v_or_b32_e32 v46, 0x60, v174
	v_bitop3_b32 v46, v46, v56, v57 bitop3:0xde
	v_add_u32_e32 v180, 0, v46
	ds_read_b128 v[46:49], v180 offset:32768
	s_waitcnt lgkmcnt(0)
	v_mfma_f32_32x32x16_bf16 v[30:45], v[46:49], v[114:117], v[30:45]
	ds_read_b128 v[46:49], v180 offset:40960
	s_waitcnt lgkmcnt(0)
	v_mfma_f32_32x32x16_bf16 v[14:29], v[46:49], v[114:117], v[14:29]
	v_or_b32_e32 v46, 0x80, v174
	v_bitop3_b32 v46, v46, v56, v57 bitop3:0xde
	v_add_u32_e32 v181, 0, v46
	ds_read_b128 v[46:49], v181 offset:32768
	ds_read_b128 v[52:55], v181 offset:40960
	s_waitcnt lgkmcnt(1)
	v_mfma_f32_32x32x16_bf16 v[30:45], v[46:49], v[110:113], v[30:45]
	v_or_b32_e32 v46, 0xa0, v174
	v_bitop3_b32 v46, v46, v56, v57 bitop3:0xde
	v_add_u32_e32 v178, 0, v46
	v_lshlrev_b64 v[46:47], 12, v[60:61]
	v_lshl_add_u64 v[46:47], s[12:13], 0, v[46:47]
	v_lshl_add_u64 v[50:51], v[62:63], 1, v[46:47]
	v_add_co_u32_e32 v46, vcc, 0x40000, v50
	ds_read_b128 v[68:71], v178 offset:32768
	s_nop 0
	v_addc_co_u32_e32 v47, vcc, 0, v51, vcc
	global_load_dwordx4 v[46:49], v[46:47], off
	s_waitcnt lgkmcnt(1)
	v_mfma_f32_32x32x16_bf16 v[14:29], v[52:55], v[110:113], v[14:29]
	ds_read_b128 v[52:55], v178 offset:40960
	v_bitop3_b32 v56, v64, v56, v57 bitop3:0xde
	v_add_u32_e32 v184, 0, v56
	s_waitcnt lgkmcnt(0)
	v_mfma_f32_32x32x16_bf16 v[14:29], v[52:55], v[8:11], v[14:29]
	ds_read_b128 v[52:55], v185 offset:32768
	v_mfma_f32_32x32x16_bf16 v[30:45], v[68:71], v[8:11], v[30:45]
	s_waitcnt lgkmcnt(0)
	v_mfma_f32_32x32x16_bf16 v[30:45], v[52:55], v[4:7], v[30:45]
	ds_read_b128 v[52:55], v184 offset:32768
	s_waitcnt lgkmcnt(0)
	v_mfma_f32_32x32x16_bf16 v[30:45], v[52:55], v[0:3], v[30:45]
	ds_read_b128 v[52:55], v185 offset:40960
	ds_read_b128 v[68:71], v184 offset:40960
	s_waitcnt lgkmcnt(1)
	v_mfma_f32_32x32x16_bf16 v[14:29], v[52:55], v[4:7], v[14:29]
	s_nop 7
	v_max_f32_e32 v56, v31, v31
	v_max_f32_e32 v57, v30, v30
	v_max_f32_e32 v56, v57, v56
	v_max3_f32 v52, v56, v32, v33
	v_max3_f32 v52, v52, v34, v35
	v_max3_f32 v52, v52, v36, v37
	v_max3_f32 v52, v52, v38, v39
	s_waitcnt lgkmcnt(0)
	v_mfma_f32_32x32x16_bf16 v[14:29], v[68:71], v[0:3], v[14:29]
	v_max3_f32 v52, v52, v40, v41
	v_max3_f32 v52, v52, v42, v43
	v_max3_f32 v52, v52, v44, v45
	v_add_u32_e32 v54, 64, v58
	s_nop 7
	v_max3_f32 v52, v52, v14, v15
	v_max3_f32 v52, v52, v16, v17
	v_max3_f32 v52, v52, v18, v19
	v_max3_f32 v52, v52, v20, v21
	v_max3_f32 v52, v52, v22, v23
	v_max3_f32 v52, v52, v24, v25
	v_max3_f32 v52, v52, v26, v27
	v_max3_f32 v52, v52, v28, v29
	v_mov_b32_e32 v53, v52
	s_nop 1
	v_permlane32_swap_b32_e32 v52, v53
	v_max_f32_e32 v53, v53, v53
	v_max_f32_e32 v52, v52, v52
	v_max_f32_e32 v72, v52, v53
	v_add_f32_e32 v52, 0x7149f2ca, v72
	v_cmp_ge_f32_e64 s[40:41], s81, v52
	s_and_saveexec_b64 s[14:15], s[42:43]
	s_xor_b64 s[14:15], exec, s[14:15]
	v_mov_b32_e32 v55, v12
	v_lshlrev_b64 v[52:53], 12, v[54:55]
	s_or_saveexec_b64 s[14:15], s[14:15]
	s_xor_b64 exec, exec, s[14:15]
	s_cbranch_execz .LBB0_1054
	v_ashrrev_i32_e32 v55, 31, v54
	v_lshlrev_b64 v[52:53], 12, v[54:55]
	v_lshl_add_u64 v[54:55], s[12:13], 0, v[52:53]
	v_lshl_add_u64 v[54:55], v[66:67], 1, v[54:55]
	global_load_dwordx4 v[130:133], v[54:55], off
